# combo + D2 stagger: WGs with bid bit4 sleep ~8k cycles before the residual phase
# baseline (speedup 1.0000x reference)
; __global__ void __launch_bounds__(256, 2) hybrid_megakernel(Params p) {
;     ...
;     xcd_barrier(xg);
;     for (int it = bid; it < 512; it += nb) outproj_item(p, l, it, lds);
;     xcd_barrier(xg);
;     const float* xin = (l == 0) ? p.x : p.out;
;     for (int vb = bid; vb < 512; vb += nb)
;       for (int j = vb >> 3; j < 128; j += 64) resid_rows<4>(p, l, (vb & 7) * 2048 + j * 16 + wid * 4, xin);
.LBB0_587:
	s_or_b64 exec, exec, s[0:1]
	v_readlane_b32 s0, v234, 27
	v_readlane_b32 s1, v234, 28
	s_and_b64 vcc, exec, s[0:1]
	s_waitcnt lgkmcnt(0)
	s_barrier
	s_cbranch_vccnz .LBB0_632
	v_readlane_b32 s16, v235, 0
	s_nop 1
	s_lshr_b32 s16, s16, 4
	s_and_b32 s16, s16, 1
	s_cmp_eq_u32 s16, 0
	s_cbranch_scc1 .Ld2_nostag
	s_sleep 127
.Ld2_nostag:
	v_readlane_b32 s16, v234, 24
	v_readlane_b32 s0, v235, 1
	s_cmp_eq_u32 s16, 0
	v_readlane_b32 s1, v235, 2
	v_readlane_b32 s2, v235, 3
	v_readlane_b32 s3, v235, 4
	s_cselect_b32 s1, s1, s89
	s_cselect_b32 s0, s0, s88
	s_lshl_b32 s80, s16, 10
	s_lshl_b64 s[2:3], s[80:81], 2
	s_add_u32 s2, s86, s2
	s_addc_u32 s3, s87, s3
	v_readlane_b32 s4, v235, 5
	v_readlane_b32 s5, v235, 6
	v_readlane_b32 s12, v235, 13
	v_readlane_b32 s13, v235, 14
	s_cmp_lg_u32 s16, 3
	s_cselect_b64 s[4:5], -1, 0
	v_readlane_b32 s12, v234, 16
	v_readlane_b32 s13, v235, 0
	v_readlane_b32 s6, v235, 7
	v_readlane_b32 s7, v235, 8
	v_readlane_b32 s8, v235, 9
	v_readlane_b32 s9, v235, 10
	v_readlane_b32 s10, v235, 11
	v_readlane_b32 s11, v235, 12
	v_readlane_b32 s14, v235, 15
	v_readlane_b32 s15, v235, 16
	s_branch .LBB0_590
